# static s_setprio 1 for waves 0-3 in the GEMM K-loops (mirror), per-block flips deleted
# baseline (speedup 1.0000x reference)
.LBB0_450:
	s_ashr_i32 s21, s20, 31
	s_lshl_b64 s[24:25], s[20:21], 19
	s_add_u32 s24, s2, s24
	s_addc_u32 s25, s3, s25
	s_and_b64 s[26:27], s[10:11], exec
	s_cselect_b32 s21, s25, s31
	s_cselect_b32 s84, s24, s30
	s_ashr_i32 s13, s12, 31
	s_lshl_b64 s[26:27], s[12:13], 19
	s_add_u32 s26, s18, s26
	s_addc_u32 s27, s19, s27
	s_and_b64 s[34:35], s[10:11], exec
	s_cselect_b32 s13, s27, s29
	s_cselect_b32 s85, s26, s28
	s_add_u32 s86, s28, 0x100
	s_addc_u32 s87, s29, 0
	s_add_u32 s28, s30, 0x40080
	v_mov_b32_e32 v2, 0
	s_addc_u32 s29, s31, 0
	s_mov_b32 s88, -2
	v_mov_b32_e32 v3, v2
	v_mov_b32_e32 v4, v2
	v_mov_b32_e32 v5, v2
	v_mov_b32_e32 v6, v2
	v_mov_b32_e32 v7, v2
	v_mov_b32_e32 v8, v2
	v_mov_b32_e32 v9, v2
	v_mov_b32_e32 v10, v2
	v_mov_b32_e32 v11, v2
	v_mov_b32_e32 v12, v2
	v_mov_b32_e32 v13, v2
	v_mov_b32_e32 v14, v2
	v_mov_b32_e32 v15, v2
	v_mov_b32_e32 v16, v2
	v_mov_b32_e32 v17, v2
	v_mov_b32_e32 v26, v2
	v_mov_b32_e32 v27, v2
	v_mov_b32_e32 v28, v2
	v_mov_b32_e32 v29, v2
	v_mov_b32_e32 v30, v2
	v_mov_b32_e32 v31, v2
	v_mov_b32_e32 v32, v2
	v_mov_b32_e32 v33, v2
	v_mov_b32_e32 v42, v2
	v_mov_b32_e32 v43, v2
	v_mov_b32_e32 v44, v2
	v_mov_b32_e32 v45, v2
	v_mov_b32_e32 v46, v2
	v_mov_b32_e32 v47, v2
	v_mov_b32_e32 v48, v2
	v_mov_b32_e32 v49, v2
	v_mov_b32_e32 v18, v2
	v_mov_b32_e32 v19, v2
	v_mov_b32_e32 v20, v2
	v_mov_b32_e32 v21, v2
	v_mov_b32_e32 v22, v2
	v_mov_b32_e32 v23, v2
	v_mov_b32_e32 v24, v2
	v_mov_b32_e32 v25, v2
	v_mov_b32_e32 v34, v2
	v_mov_b32_e32 v35, v2
	v_mov_b32_e32 v36, v2
	v_mov_b32_e32 v37, v2
	v_mov_b32_e32 v38, v2
	v_mov_b32_e32 v39, v2
	v_mov_b32_e32 v40, v2
	v_mov_b32_e32 v41, v2
	v_mov_b32_e32 v50, v2
	v_mov_b32_e32 v51, v2
	v_mov_b32_e32 v52, v2
	v_mov_b32_e32 v53, v2
	v_mov_b32_e32 v54, v2
	v_mov_b32_e32 v55, v2
	v_mov_b32_e32 v56, v2
	v_mov_b32_e32 v57, v2
	v_mov_b32_e32 v58, v2
	v_mov_b32_e32 v59, v2
	v_mov_b32_e32 v60, v2
	v_mov_b32_e32 v61, v2
	v_mov_b32_e32 v62, v2
	v_mov_b32_e32 v63, v2
	v_mov_b32_e32 v64, v2
	v_mov_b32_e32 v65, v2
	v_mov_b32_e32 v66, v2
	v_mov_b32_e32 v67, v2
	v_mov_b32_e32 v68, v2
	v_mov_b32_e32 v69, v2
	v_mov_b32_e32 v70, v2
	v_mov_b32_e32 v71, v2
	v_mov_b32_e32 v72, v2
	v_mov_b32_e32 v73, v2
	v_mov_b32_e32 v74, v2
	v_mov_b32_e32 v75, v2
	v_mov_b32_e32 v76, v2
	v_mov_b32_e32 v77, v2
	v_mov_b32_e32 v78, v2
	v_mov_b32_e32 v79, v2
	v_mov_b32_e32 v80, v2
	v_mov_b32_e32 v81, v2
	v_mov_b32_e32 v86, v2
	v_mov_b32_e32 v87, v2
	v_mov_b32_e32 v88, v2
	v_mov_b32_e32 v89, v2
	v_mov_b32_e32 v94, v2
	v_mov_b32_e32 v95, v2
	v_mov_b32_e32 v96, v2
	v_mov_b32_e32 v97, v2
	v_mov_b32_e32 v102, v2
	v_mov_b32_e32 v103, v2
	v_mov_b32_e32 v104, v2
	v_mov_b32_e32 v105, v2
	v_mov_b32_e32 v110, v2
	v_mov_b32_e32 v111, v2
	v_mov_b32_e32 v112, v2
	v_mov_b32_e32 v113, v2
	v_mov_b32_e32 v82, v2
	v_mov_b32_e32 v83, v2
	v_mov_b32_e32 v84, v2
	v_mov_b32_e32 v85, v2
	v_mov_b32_e32 v90, v2
	v_mov_b32_e32 v91, v2
	v_mov_b32_e32 v92, v2
	v_mov_b32_e32 v93, v2
	v_mov_b32_e32 v98, v2
	v_mov_b32_e32 v99, v2
	v_mov_b32_e32 v100, v2
	v_mov_b32_e32 v101, v2
	v_mov_b32_e32 v106, v2
	v_mov_b32_e32 v107, v2
	v_mov_b32_e32 v108, v2
	v_mov_b32_e32 v109, v2
	v_mov_b32_e32 v114, v2
	v_mov_b32_e32 v115, v2
	v_mov_b32_e32 v116, v2
	v_mov_b32_e32 v117, v2
	v_mov_b32_e32 v118, v2
	v_mov_b32_e32 v119, v2
	v_mov_b32_e32 v120, v2
	v_mov_b32_e32 v121, v2
	v_mov_b32_e32 v122, v2
	v_mov_b32_e32 v123, v2
	v_mov_b32_e32 v124, v2
	v_mov_b32_e32 v125, v2
	v_mov_b32_e32 v126, v2
	v_mov_b32_e32 v127, v2
	v_mov_b32_e32 v128, v2
	v_mov_b32_e32 v129, v2
	v_readfirstlane_b32 vcc_lo, v169
	s_nop 0
	s_bitcmp1_b32 vcc_lo, 8
	s_cbranch_scc1 .Lprio_skip_cm
	s_setprio 1

.LBB0_591:
	s_ashr_i32 s77, s76, 31
	s_lshl_b64 s[8:9], s[76:77], 19
	v_readlane_b32 s26, v254, 21
	v_readlane_b32 s27, v254, 22
	s_add_u32 s78, s26, s8
	s_addc_u32 s79, s27, s9
	s_and_b64 s[8:9], s[2:3], exec
	s_cselect_b32 s1, s79, s25
	s_cselect_b32 s26, s78, s24
	s_ashr_i32 s75, s74, 31
	s_lshl_b64 s[8:9], s[74:75], 19
	v_readlane_b32 s28, v254, 39
	v_readlane_b32 s29, v254, 40
	s_add_u32 s80, s28, s8
	s_addc_u32 s81, s29, s9
	s_and_b64 s[8:9], s[2:3], exec
	s_cselect_b32 s27, s81, s5
	s_cselect_b32 s28, s80, s4
	s_add_u32 s29, s4, 0x100
	s_addc_u32 s34, s5, 0
	s_add_u32 s4, s24, 0x40080
	v_mov_b32_e32 v2, 0
	s_addc_u32 s5, s25, 0
	s_mov_b32 s35, -2
	v_mov_b32_e32 v3, v2
	v_mov_b32_e32 v4, v2
	v_mov_b32_e32 v5, v2
	v_mov_b32_e32 v6, v2
	v_mov_b32_e32 v7, v2
	v_mov_b32_e32 v8, v2
	v_mov_b32_e32 v9, v2
	v_mov_b32_e32 v18, v2
	v_mov_b32_e32 v19, v2
	v_mov_b32_e32 v20, v2
	v_mov_b32_e32 v21, v2
	v_mov_b32_e32 v22, v2
	v_mov_b32_e32 v23, v2
	v_mov_b32_e32 v24, v2
	v_mov_b32_e32 v25, v2
	v_mov_b32_e32 v34, v2
	v_mov_b32_e32 v35, v2
	v_mov_b32_e32 v36, v2
	v_mov_b32_e32 v37, v2
	v_mov_b32_e32 v38, v2
	v_mov_b32_e32 v39, v2
	v_mov_b32_e32 v40, v2
	v_mov_b32_e32 v41, v2
	v_mov_b32_e32 v50, v2
	v_mov_b32_e32 v51, v2
	v_mov_b32_e32 v52, v2
	v_mov_b32_e32 v53, v2
	v_mov_b32_e32 v54, v2
	v_mov_b32_e32 v55, v2
	v_mov_b32_e32 v56, v2
	v_mov_b32_e32 v57, v2
	v_mov_b32_e32 v10, v2
	v_mov_b32_e32 v11, v2
	v_mov_b32_e32 v12, v2
	v_mov_b32_e32 v13, v2
	v_mov_b32_e32 v14, v2
	v_mov_b32_e32 v15, v2
	v_mov_b32_e32 v16, v2
	v_mov_b32_e32 v17, v2
	v_mov_b32_e32 v26, v2
	v_mov_b32_e32 v27, v2
	v_mov_b32_e32 v28, v2
	v_mov_b32_e32 v29, v2
	v_mov_b32_e32 v30, v2
	v_mov_b32_e32 v31, v2
	v_mov_b32_e32 v32, v2
	v_mov_b32_e32 v33, v2
	v_mov_b32_e32 v42, v2
	v_mov_b32_e32 v43, v2
	v_mov_b32_e32 v44, v2
	v_mov_b32_e32 v45, v2
	v_mov_b32_e32 v46, v2
	v_mov_b32_e32 v47, v2
	v_mov_b32_e32 v48, v2
	v_mov_b32_e32 v49, v2
	v_mov_b32_e32 v58, v2
	v_mov_b32_e32 v59, v2
	v_mov_b32_e32 v60, v2
	v_mov_b32_e32 v61, v2
	v_mov_b32_e32 v62, v2
	v_mov_b32_e32 v63, v2
	v_mov_b32_e32 v64, v2
	v_mov_b32_e32 v65, v2
	v_mov_b32_e32 v66, v2
	v_mov_b32_e32 v67, v2
	v_mov_b32_e32 v68, v2
	v_mov_b32_e32 v69, v2
	v_mov_b32_e32 v70, v2
	v_mov_b32_e32 v71, v2
	v_mov_b32_e32 v72, v2
	v_mov_b32_e32 v73, v2
	v_mov_b32_e32 v82, v2
	v_mov_b32_e32 v83, v2
	v_mov_b32_e32 v84, v2
	v_mov_b32_e32 v85, v2
	v_mov_b32_e32 v86, v2
	v_mov_b32_e32 v87, v2
	v_mov_b32_e32 v88, v2
	v_mov_b32_e32 v89, v2
	v_mov_b32_e32 v98, v2
	v_mov_b32_e32 v99, v2
	v_mov_b32_e32 v100, v2
	v_mov_b32_e32 v101, v2
	v_mov_b32_e32 v102, v2
	v_mov_b32_e32 v103, v2
	v_mov_b32_e32 v104, v2
	v_mov_b32_e32 v105, v2
	v_mov_b32_e32 v114, v2
	v_mov_b32_e32 v115, v2
	v_mov_b32_e32 v116, v2
	v_mov_b32_e32 v117, v2
	v_mov_b32_e32 v118, v2
	v_mov_b32_e32 v119, v2
	v_mov_b32_e32 v120, v2
	v_mov_b32_e32 v121, v2
	v_mov_b32_e32 v74, v2
	v_mov_b32_e32 v75, v2
	v_mov_b32_e32 v76, v2
	v_mov_b32_e32 v77, v2
	v_mov_b32_e32 v78, v2
	v_mov_b32_e32 v79, v2
	v_mov_b32_e32 v80, v2
	v_mov_b32_e32 v81, v2
	v_mov_b32_e32 v90, v2
	v_mov_b32_e32 v91, v2
	v_mov_b32_e32 v92, v2
	v_mov_b32_e32 v93, v2
	v_mov_b32_e32 v94, v2
	v_mov_b32_e32 v95, v2
	v_mov_b32_e32 v96, v2
	v_mov_b32_e32 v97, v2
	v_mov_b32_e32 v106, v2
	v_mov_b32_e32 v107, v2
	v_mov_b32_e32 v108, v2
	v_mov_b32_e32 v109, v2
	v_mov_b32_e32 v110, v2
	v_mov_b32_e32 v111, v2
	v_mov_b32_e32 v112, v2
	v_mov_b32_e32 v113, v2
	v_mov_b32_e32 v122, v2
	v_mov_b32_e32 v123, v2
	v_mov_b32_e32 v124, v2
	v_mov_b32_e32 v125, v2
	v_mov_b32_e32 v126, v2
	v_mov_b32_e32 v127, v2
	v_mov_b32_e32 v128, v2
	v_mov_b32_e32 v129, v2
	v_readfirstlane_b32 vcc_lo, v169
	s_nop 0
	s_bitcmp1_b32 vcc_lo, 8
	s_cbranch_scc1 .Lprio_skip_ip
	s_setprio 1

.LBB0_899:
	s_add_u32 s71, s24, 0x100
	v_mov_b32_e32 v2, 0
	s_addc_u32 s72, s25, 0
	s_mov_b32 s73, -2
	s_waitcnt lgkmcnt(0)
	v_mov_b32_e32 v3, v2
	v_mov_b32_e32 v4, v2
	v_mov_b32_e32 v5, v2
	v_mov_b32_e32 v6, v2
	v_mov_b32_e32 v7, v2
	v_mov_b32_e32 v8, v2
	v_mov_b32_e32 v9, v2
	v_mov_b32_e32 v18, v2
	v_mov_b32_e32 v19, v2
	v_mov_b32_e32 v20, v2
	v_mov_b32_e32 v21, v2
	v_mov_b32_e32 v22, v2
	v_mov_b32_e32 v23, v2
	v_mov_b32_e32 v24, v2
	v_mov_b32_e32 v25, v2
	v_mov_b32_e32 v34, v2
	v_mov_b32_e32 v35, v2
	v_mov_b32_e32 v36, v2
	v_mov_b32_e32 v37, v2
	v_mov_b32_e32 v38, v2
	v_mov_b32_e32 v39, v2
	v_mov_b32_e32 v40, v2
	v_mov_b32_e32 v41, v2
	s_waitcnt lgkmcnt(0)
	v_mov_b32_e32 v50, v2
	v_mov_b32_e32 v51, v2
	v_mov_b32_e32 v52, v2
	v_mov_b32_e32 v53, v2
	v_mov_b32_e32 v54, v2
	v_mov_b32_e32 v55, v2
	v_mov_b32_e32 v56, v2
	v_mov_b32_e32 v57, v2
	v_mov_b32_e32 v10, v2
	v_mov_b32_e32 v11, v2
	v_mov_b32_e32 v12, v2
	v_mov_b32_e32 v13, v2
	v_mov_b32_e32 v14, v2
	v_mov_b32_e32 v15, v2
	v_mov_b32_e32 v16, v2
	v_mov_b32_e32 v17, v2
	v_mov_b32_e32 v26, v2
	v_mov_b32_e32 v27, v2
	v_mov_b32_e32 v28, v2
	v_mov_b32_e32 v29, v2
	v_mov_b32_e32 v30, v2
	v_mov_b32_e32 v31, v2
	v_mov_b32_e32 v32, v2
	v_mov_b32_e32 v33, v2
	v_mov_b32_e32 v42, v2
	v_mov_b32_e32 v43, v2
	v_mov_b32_e32 v44, v2
	v_mov_b32_e32 v45, v2
	v_mov_b32_e32 v46, v2
	v_mov_b32_e32 v47, v2
	v_mov_b32_e32 v48, v2
	v_mov_b32_e32 v49, v2
	v_mov_b32_e32 v58, v2
	v_mov_b32_e32 v59, v2
	v_mov_b32_e32 v60, v2
	v_mov_b32_e32 v61, v2
	v_mov_b32_e32 v62, v2
	v_mov_b32_e32 v63, v2
	v_mov_b32_e32 v64, v2
	v_mov_b32_e32 v65, v2
	v_mov_b32_e32 v66, v2
	v_mov_b32_e32 v67, v2
	v_mov_b32_e32 v68, v2
	v_mov_b32_e32 v69, v2
	v_mov_b32_e32 v70, v2
	v_mov_b32_e32 v71, v2
	v_mov_b32_e32 v72, v2
	v_mov_b32_e32 v73, v2
	v_mov_b32_e32 v82, v2
	v_mov_b32_e32 v83, v2
	v_mov_b32_e32 v84, v2
	v_mov_b32_e32 v85, v2
	v_mov_b32_e32 v86, v2
	v_mov_b32_e32 v87, v2
	v_mov_b32_e32 v88, v2
	v_mov_b32_e32 v89, v2
	v_mov_b32_e32 v98, v2
	v_mov_b32_e32 v99, v2
	v_mov_b32_e32 v100, v2
	v_mov_b32_e32 v101, v2
	v_mov_b32_e32 v102, v2
	v_mov_b32_e32 v103, v2
	v_mov_b32_e32 v104, v2
	v_mov_b32_e32 v105, v2
	v_mov_b32_e32 v114, v2
	v_mov_b32_e32 v115, v2
	v_mov_b32_e32 v116, v2
	v_mov_b32_e32 v117, v2
	v_mov_b32_e32 v118, v2
	v_mov_b32_e32 v119, v2
	v_mov_b32_e32 v120, v2
	v_mov_b32_e32 v121, v2
	v_mov_b32_e32 v74, v2
	v_mov_b32_e32 v75, v2
	v_mov_b32_e32 v76, v2
	v_mov_b32_e32 v77, v2
	v_mov_b32_e32 v78, v2
	v_mov_b32_e32 v79, v2
	v_mov_b32_e32 v80, v2
	v_mov_b32_e32 v81, v2
	v_mov_b32_e32 v90, v2
	v_mov_b32_e32 v91, v2
	v_mov_b32_e32 v92, v2
	v_mov_b32_e32 v93, v2
	v_mov_b32_e32 v94, v2
	v_mov_b32_e32 v95, v2
	v_mov_b32_e32 v96, v2
	v_mov_b32_e32 v97, v2
	v_mov_b32_e32 v106, v2
	v_mov_b32_e32 v107, v2
	v_mov_b32_e32 v108, v2
	v_mov_b32_e32 v109, v2
	v_mov_b32_e32 v110, v2
	v_mov_b32_e32 v111, v2
	v_mov_b32_e32 v112, v2
	v_mov_b32_e32 v113, v2
	v_mov_b32_e32 v122, v2
	v_mov_b32_e32 v123, v2
	v_mov_b32_e32 v124, v2
	v_mov_b32_e32 v125, v2
	v_mov_b32_e32 v126, v2
	v_mov_b32_e32 v127, v2
	v_mov_b32_e32 v128, v2
	v_mov_b32_e32 v129, v2
	v_readfirstlane_b32 vcc_lo, v169
	s_nop 0
	s_bitcmp1_b32 vcc_lo, 8
	s_cbranch_scc1 .Lprio_skip_dn
	s_setprio 1

.LBB0_959:
	s_ashr_i32 s11, s10, 31
	s_lshl_b64 s[12:13], s[10:11], 19
	s_add_u32 s12, s29, s12
	s_addc_u32 s13, s19, s13
	s_and_b64 s[16:17], s[2:3], exec
	s_cselect_b32 s11, s13, s25
	s_cselect_b32 s67, s12, s24
	s_ashr_i32 s7, s6, 31
	s_lshl_b64 s[16:17], s[6:7], 19
	s_add_u32 s16, s30, s16
	s_addc_u32 s17, s31, s17
	s_and_b64 s[26:27], s[2:3], exec
	s_cselect_b32 s7, s17, s21
	s_cselect_b32 s68, s16, s20
	s_add_u32 s69, s20, 0x100
	s_addc_u32 s70, s21, 0
	s_add_u32 s20, s24, 0x40080
	v_mov_b32_e32 v2, 0
	s_addc_u32 s21, s25, 0
	s_mov_b32 s71, -2
	v_mov_b32_e32 v3, v2
	v_mov_b32_e32 v4, v2
	v_mov_b32_e32 v5, v2
	v_mov_b32_e32 v10, v2
	v_mov_b32_e32 v11, v2
	v_mov_b32_e32 v12, v2
	v_mov_b32_e32 v13, v2
	v_mov_b32_e32 v18, v2
	v_mov_b32_e32 v19, v2
	v_mov_b32_e32 v20, v2
	v_mov_b32_e32 v21, v2
	v_mov_b32_e32 v26, v2
	v_mov_b32_e32 v27, v2
	v_mov_b32_e32 v28, v2
	v_mov_b32_e32 v29, v2
	v_mov_b32_e32 v34, v2
	v_mov_b32_e32 v35, v2
	v_mov_b32_e32 v36, v2
	v_mov_b32_e32 v37, v2
	v_mov_b32_e32 v42, v2
	v_mov_b32_e32 v43, v2
	v_mov_b32_e32 v44, v2
	v_mov_b32_e32 v45, v2
	v_mov_b32_e32 v50, v2
	v_mov_b32_e32 v51, v2
	v_mov_b32_e32 v52, v2
	v_mov_b32_e32 v53, v2
	v_mov_b32_e32 v58, v2
	v_mov_b32_e32 v59, v2
	v_mov_b32_e32 v60, v2
	v_mov_b32_e32 v61, v2
	v_mov_b32_e32 v6, v2
	v_mov_b32_e32 v7, v2
	v_mov_b32_e32 v8, v2
	v_mov_b32_e32 v9, v2
	v_mov_b32_e32 v14, v2
	v_mov_b32_e32 v15, v2
	v_mov_b32_e32 v16, v2
	v_mov_b32_e32 v17, v2
	v_mov_b32_e32 v22, v2
	v_mov_b32_e32 v23, v2
	v_mov_b32_e32 v24, v2
	v_mov_b32_e32 v25, v2
	v_mov_b32_e32 v30, v2
	v_mov_b32_e32 v31, v2
	v_mov_b32_e32 v32, v2
	v_mov_b32_e32 v33, v2
	v_mov_b32_e32 v38, v2
	v_mov_b32_e32 v39, v2
	v_mov_b32_e32 v40, v2
	v_mov_b32_e32 v41, v2
	v_mov_b32_e32 v46, v2
	v_mov_b32_e32 v47, v2
	v_mov_b32_e32 v48, v2
	v_mov_b32_e32 v49, v2
	v_mov_b32_e32 v54, v2
	v_mov_b32_e32 v55, v2
	v_mov_b32_e32 v56, v2
	v_mov_b32_e32 v57, v2
	v_mov_b32_e32 v62, v2
	v_mov_b32_e32 v63, v2
	v_mov_b32_e32 v64, v2
	v_mov_b32_e32 v65, v2
	v_mov_b32_e32 v66, v2
	v_mov_b32_e32 v67, v2
	v_mov_b32_e32 v68, v2
	v_mov_b32_e32 v69, v2
	v_mov_b32_e32 v74, v2
	v_mov_b32_e32 v75, v2
	v_mov_b32_e32 v76, v2
	v_mov_b32_e32 v77, v2
	v_mov_b32_e32 v82, v2
	v_mov_b32_e32 v83, v2
	v_mov_b32_e32 v84, v2
	v_mov_b32_e32 v85, v2
	v_mov_b32_e32 v90, v2
	v_mov_b32_e32 v91, v2
	v_mov_b32_e32 v92, v2
	v_mov_b32_e32 v93, v2
	v_mov_b32_e32 v98, v2
	v_mov_b32_e32 v99, v2
	v_mov_b32_e32 v100, v2
	v_mov_b32_e32 v101, v2
	v_mov_b32_e32 v106, v2
	v_mov_b32_e32 v107, v2
	v_mov_b32_e32 v108, v2
	v_mov_b32_e32 v109, v2
	v_mov_b32_e32 v114, v2
	v_mov_b32_e32 v115, v2
	v_mov_b32_e32 v116, v2
	v_mov_b32_e32 v117, v2
	v_mov_b32_e32 v122, v2
	v_mov_b32_e32 v123, v2
	v_mov_b32_e32 v124, v2
	v_mov_b32_e32 v125, v2
	v_mov_b32_e32 v70, v2
	v_mov_b32_e32 v71, v2
	v_mov_b32_e32 v72, v2
	v_mov_b32_e32 v73, v2
	v_mov_b32_e32 v78, v2
	v_mov_b32_e32 v79, v2
	v_mov_b32_e32 v80, v2
	v_mov_b32_e32 v81, v2
	v_mov_b32_e32 v86, v2
	v_mov_b32_e32 v87, v2
	v_mov_b32_e32 v88, v2
	v_mov_b32_e32 v89, v2
	v_mov_b32_e32 v94, v2
	v_mov_b32_e32 v95, v2
	v_mov_b32_e32 v96, v2
	v_mov_b32_e32 v97, v2
	v_mov_b32_e32 v102, v2
	v_mov_b32_e32 v103, v2
	v_mov_b32_e32 v104, v2
	v_mov_b32_e32 v105, v2
	v_mov_b32_e32 v110, v2
	v_mov_b32_e32 v111, v2
	v_mov_b32_e32 v112, v2
	v_mov_b32_e32 v113, v2
	v_mov_b32_e32 v118, v2
	v_mov_b32_e32 v119, v2
	v_mov_b32_e32 v120, v2
	v_mov_b32_e32 v121, v2
	v_mov_b32_e32 v126, v2
	v_mov_b32_e32 v127, v2
	v_mov_b32_e32 v128, v2
	v_mov_b32_e32 v129, v2
	v_readfirstlane_b32 vcc_lo, v169
	s_nop 0
	s_bitcmp1_b32 vcc_lo, 8
	s_cbranch_scc1 .Lprio_skip_gu
	s_setprio 1

.LBB0_992:
	s_ashr_i32 s19, s18, 31
	s_lshl_b64 s[20:21], s[18:19], 19
	v_readlane_b32 s30, v254, 21
	v_readlane_b32 s31, v254, 22
	s_add_u32 s20, s30, s20
	s_addc_u32 s21, s31, s21
	s_and_b64 s[30:31], s[4:5], exec
	s_cselect_b32 s19, s21, s29
	s_cselect_b32 s25, s20, s28
	s_ashr_i32 s17, s16, 31
	s_lshl_b64 s[30:31], s[16:17], 19
	s_add_u32 s38, s0, s30
	s_addc_u32 s39, s1, s31
	s_and_b64 s[30:31], s[4:5], exec
	s_cselect_b32 s17, s39, s27
	s_cselect_b32 s71, s38, s26
	s_add_u32 s73, s26, 0x100
	s_addc_u32 s74, s27, 0
	s_add_u32 s26, s28, 0x40080
	v_mov_b32_e32 v2, 0
	s_addc_u32 s27, s29, 0
	s_mov_b32 s75, -2
	s_waitcnt lgkmcnt(0)
	v_mov_b32_e32 v3, v2
	v_mov_b32_e32 v4, v2
	v_mov_b32_e32 v5, v2
	v_mov_b32_e32 v6, v2
	v_mov_b32_e32 v7, v2
	v_mov_b32_e32 v8, v2
	v_mov_b32_e32 v9, v2
	v_mov_b32_e32 v18, v2
	v_mov_b32_e32 v19, v2
	v_mov_b32_e32 v20, v2
	v_mov_b32_e32 v21, v2
	v_mov_b32_e32 v22, v2
	v_mov_b32_e32 v23, v2
	v_mov_b32_e32 v24, v2
	v_mov_b32_e32 v25, v2
	v_mov_b32_e32 v34, v2
	v_mov_b32_e32 v35, v2
	v_mov_b32_e32 v36, v2
	v_mov_b32_e32 v37, v2
	v_mov_b32_e32 v38, v2
	v_mov_b32_e32 v39, v2
	v_mov_b32_e32 v40, v2
	v_mov_b32_e32 v41, v2
	v_mov_b32_e32 v50, v2
	v_mov_b32_e32 v51, v2
	v_mov_b32_e32 v52, v2
	v_mov_b32_e32 v53, v2
	v_mov_b32_e32 v54, v2
	v_mov_b32_e32 v55, v2
	v_mov_b32_e32 v56, v2
	v_mov_b32_e32 v57, v2
	v_mov_b32_e32 v10, v2
	v_mov_b32_e32 v11, v2
	v_mov_b32_e32 v12, v2
	v_mov_b32_e32 v13, v2
	v_mov_b32_e32 v14, v2
	v_mov_b32_e32 v15, v2
	v_mov_b32_e32 v16, v2
	v_mov_b32_e32 v17, v2
	v_mov_b32_e32 v26, v2
	v_mov_b32_e32 v27, v2
	v_mov_b32_e32 v28, v2
	v_mov_b32_e32 v29, v2
	v_mov_b32_e32 v30, v2
	v_mov_b32_e32 v31, v2
	v_mov_b32_e32 v32, v2
	v_mov_b32_e32 v33, v2
	v_mov_b32_e32 v42, v2
	v_mov_b32_e32 v43, v2
	v_mov_b32_e32 v44, v2
	v_mov_b32_e32 v45, v2
	v_mov_b32_e32 v46, v2
	v_mov_b32_e32 v47, v2
	v_mov_b32_e32 v48, v2
	v_mov_b32_e32 v49, v2
	v_mov_b32_e32 v58, v2
	v_mov_b32_e32 v59, v2
	v_mov_b32_e32 v60, v2
	v_mov_b32_e32 v61, v2
	v_mov_b32_e32 v62, v2
	v_mov_b32_e32 v63, v2
	v_mov_b32_e32 v64, v2
	v_mov_b32_e32 v65, v2
	v_mov_b32_e32 v66, v2
	v_mov_b32_e32 v67, v2
	v_mov_b32_e32 v68, v2
	v_mov_b32_e32 v69, v2
	v_mov_b32_e32 v70, v2
	v_mov_b32_e32 v71, v2
	v_mov_b32_e32 v72, v2
	v_mov_b32_e32 v73, v2
	v_mov_b32_e32 v82, v2
	v_mov_b32_e32 v83, v2
	v_mov_b32_e32 v84, v2
	v_mov_b32_e32 v85, v2
	v_mov_b32_e32 v86, v2
	v_mov_b32_e32 v87, v2
	v_mov_b32_e32 v88, v2
	v_mov_b32_e32 v89, v2
	v_mov_b32_e32 v98, v2
	v_mov_b32_e32 v99, v2
	v_mov_b32_e32 v100, v2
	v_mov_b32_e32 v101, v2
	v_mov_b32_e32 v102, v2
	v_mov_b32_e32 v103, v2
	v_mov_b32_e32 v104, v2
	v_mov_b32_e32 v105, v2
	v_mov_b32_e32 v114, v2
	v_mov_b32_e32 v115, v2
	v_mov_b32_e32 v116, v2
	v_mov_b32_e32 v117, v2
	v_mov_b32_e32 v118, v2
	v_mov_b32_e32 v119, v2
	v_mov_b32_e32 v120, v2
	v_mov_b32_e32 v121, v2
	v_mov_b32_e32 v74, v2
	v_mov_b32_e32 v75, v2
	v_mov_b32_e32 v76, v2
	v_mov_b32_e32 v77, v2
	v_mov_b32_e32 v78, v2
	v_mov_b32_e32 v79, v2
	v_mov_b32_e32 v80, v2
	v_mov_b32_e32 v81, v2
	v_mov_b32_e32 v90, v2
	v_mov_b32_e32 v91, v2
	v_mov_b32_e32 v92, v2
	v_mov_b32_e32 v93, v2
	v_mov_b32_e32 v94, v2
	v_mov_b32_e32 v95, v2
	v_mov_b32_e32 v96, v2
	v_mov_b32_e32 v97, v2
	v_mov_b32_e32 v106, v2
	v_mov_b32_e32 v107, v2
	v_mov_b32_e32 v108, v2
	v_mov_b32_e32 v109, v2
	v_mov_b32_e32 v110, v2
	v_mov_b32_e32 v111, v2
	v_mov_b32_e32 v112, v2
	v_mov_b32_e32 v113, v2
	v_mov_b32_e32 v122, v2
	v_mov_b32_e32 v123, v2
	v_mov_b32_e32 v124, v2
	v_mov_b32_e32 v125, v2
	v_mov_b32_e32 v126, v2
	v_mov_b32_e32 v127, v2
	v_mov_b32_e32 v128, v2
	v_mov_b32_e32 v129, v2
	v_readfirstlane_b32 vcc_lo, v169
	s_nop 0
	s_bitcmp1_b32 vcc_lo, 8
	s_cbranch_scc1 .Lprio_skip_op
	s_setprio 1
